# band loops: K and Q tiles fetched by coalesced LDS-DMA (whole 128-byte rows, swizzled) and read back as MFMA fragments; no register save area
# speedup vs baseline: 1.0135x; 1.0045x over previous
.Lband_entry:
	s_waitcnt vmcnt(0)
	v_lshlrev_b32_e32 v183, 2, v220
	v_add_u32_e32 v2, 0x10000, v183
	v_lshrrev_b32_e32 v183, 6, v220
	v_lshlrev_b32_e32 v183, 8, v183
	v_add_u32_e32 v183, 0x0, v183
	v_mov_b32_e32 v3, s2
	ds_write_b32 v183, v3 offset:0
	v_mov_b32_e32 v3, s3
	ds_write_b32 v183, v3 offset:4
	v_mov_b32_e32 v3, s4
	ds_write_b32 v183, v3 offset:8
	v_mov_b32_e32 v3, s5
	ds_write_b32 v183, v3 offset:12
	v_mov_b32_e32 v3, s6
	ds_write_b32 v183, v3 offset:16
	v_mov_b32_e32 v3, s7
	ds_write_b32 v183, v3 offset:20
	v_mov_b32_e32 v3, s8
	ds_write_b32 v183, v3 offset:24
	v_mov_b32_e32 v3, s9
	ds_write_b32 v183, v3 offset:28
	v_mov_b32_e32 v3, s10
	ds_write_b32 v183, v3 offset:32
	v_mov_b32_e32 v3, s11
	ds_write_b32 v183, v3 offset:36
	v_mov_b32_e32 v3, s12
	ds_write_b32 v183, v3 offset:40
	v_mov_b32_e32 v3, s13
	ds_write_b32 v183, v3 offset:44
	v_mov_b32_e32 v3, s14
	ds_write_b32 v183, v3 offset:48
	v_mov_b32_e32 v3, s15
	ds_write_b32 v183, v3 offset:52
	v_mov_b32_e32 v3, s16
	ds_write_b32 v183, v3 offset:56
	v_mov_b32_e32 v3, s17
	ds_write_b32 v183, v3 offset:60
	v_mov_b32_e32 v3, s18
	ds_write_b32 v183, v3 offset:64
	v_mov_b32_e32 v3, s19
	ds_write_b32 v183, v3 offset:68
	v_mov_b32_e32 v3, s20
	ds_write_b32 v183, v3 offset:72
	v_mov_b32_e32 v3, s21
	ds_write_b32 v183, v3 offset:76
	v_mov_b32_e32 v3, s22
	ds_write_b32 v183, v3 offset:80
	v_mov_b32_e32 v3, s23
	ds_write_b32 v183, v3 offset:84
	v_mov_b32_e32 v3, s24
	ds_write_b32 v183, v3 offset:88
	v_mov_b32_e32 v3, s25
	ds_write_b32 v183, v3 offset:92
	v_mov_b32_e32 v3, s26
	ds_write_b32 v183, v3 offset:96
	v_mov_b32_e32 v3, s27
	ds_write_b32 v183, v3 offset:100
	v_mov_b32_e32 v3, s28
	ds_write_b32 v183, v3 offset:104
	v_mov_b32_e32 v3, s29
	ds_write_b32 v183, v3 offset:108
	v_mov_b32_e32 v3, s30
	ds_write_b32 v183, v3 offset:112
	v_mov_b32_e32 v3, s34
	ds_write_b32 v183, v3 offset:116
	v_mov_b32_e32 v3, s35
	ds_write_b32 v183, v3 offset:120
	v_mov_b32_e32 v3, s36
	ds_write_b32 v183, v3 offset:124
	v_mov_b32_e32 v3, s37
	ds_write_b32 v183, v3 offset:128
	v_mov_b32_e32 v3, s38
	ds_write_b32 v183, v3 offset:132
	v_mov_b32_e32 v3, s39
	ds_write_b32 v183, v3 offset:136
	v_mov_b32_e32 v3, s40
	ds_write_b32 v183, v3 offset:140
	v_mov_b32_e32 v3, s41
	ds_write_b32 v183, v3 offset:144
	v_mov_b32_e32 v3, s42
	ds_write_b32 v183, v3 offset:148
	v_mov_b32_e32 v3, s43
	ds_write_b32 v183, v3 offset:152
	v_mov_b32_e32 v3, s44
	ds_write_b32 v183, v3 offset:156
	v_mov_b32_e32 v3, s45
	ds_write_b32 v183, v3 offset:160
	v_mov_b32_e32 v3, s46
	ds_write_b32 v183, v3 offset:164
	v_mov_b32_e32 v3, s47
	ds_write_b32 v183, v3 offset:168
	v_mov_b32_e32 v3, s48
	ds_write_b32 v183, v3 offset:172
	v_mov_b32_e32 v3, s49
	ds_write_b32 v183, v3 offset:176
	v_mov_b32_e32 v3, s50
	ds_write_b32 v183, v3 offset:180
	v_mov_b32_e32 v3, s51
	ds_write_b32 v183, v3 offset:184
	v_mov_b32_e32 v3, s52
	ds_write_b32 v183, v3 offset:188
	s_mov_b32 s52, m0
	v_mov_b32_e32 v3, s52
	ds_write_b32 v183, v3 offset:192
	v_lshrrev_b32_e32 v3, 6, v220
	s_nop 0
	v_readfirstlane_b32 s50, v3
	s_nop 3
	s_mul_i32 s50, s50, 0x4000
	s_add_i32 s50, s50, 0x800
	s_load_dwordx2 s[18:19], s[70:71], 0x98
	s_load_dwordx2 s[20:21], s[70:71], 0x58
	v_and_b32_e32 v47, 31, v173
	v_lshrrev_b32_e32 v48, 5, v173
	v_lshlrev_b32_e32 v46, 4, v173
	v_mov_b32_e32 v67, 0xff800000
	v_lshlrev_b32_e32 v183, 2, v48
	v_sub_u32_e32 v54, v47, v183
	v_mov_b32_e32 v66, 0x3e38aa3b
	v_and_b32_e32 v3, 7, v47
	v_add_u32_e32 v35, 0, v48
	v_xor_b32_e32 v35, v35, v3
	v_lshlrev_b32_e32 v35, 4, v35
	v_lshl_add_u32 v35, v47, 7, v35
	v_add_u32_e32 v35, s50, v35
	v_add_u32_e32 v36, 2, v48
	v_xor_b32_e32 v36, v36, v3
	v_lshlrev_b32_e32 v36, 4, v36
	v_lshl_add_u32 v36, v47, 7, v36
	v_add_u32_e32 v36, s50, v36
	v_add_u32_e32 v37, 4, v48
	v_xor_b32_e32 v37, v37, v3
	v_lshlrev_b32_e32 v37, 4, v37
	v_lshl_add_u32 v37, v47, 7, v37
	v_add_u32_e32 v37, s50, v37
	v_add_u32_e32 v38, 6, v48
	v_xor_b32_e32 v38, v38, v3
	v_lshlrev_b32_e32 v38, 4, v38
	v_lshl_add_u32 v38, v47, 7, v38
	v_add_u32_e32 v38, s50, v38
	v_lshrrev_b32_e32 v39, 3, v173
	v_and_b32_e32 v3, 7, v173
	v_and_b32_e32 v40, 7, v39
	v_xor_b32_e32 v40, v3, v40
	v_lshlrev_b32_e32 v40, 4, v40
	s_mov_b32 s0, s1
	s_waitcnt lgkmcnt(0)

.Lband_dec_done:
	s_mul_i32 s17, s23, 0x1600000
	s_add_u32 s2, s18, s17
	s_addc_u32 s3, s19, 0
	s_add_u32 s2, s2, 0x5600000
	s_addc_u32 s3, s3, 0
	s_lshl_b32 s11, 0x2c000, s9
	v_lshl_add_u32 v183, s8, 5, v47
	v_lshlrev_b32_e32 v183, s9, v183
	v_add_u32_e32 v57, s10, v183
	v_lshlrev_b32_e32 v183, s9, v39
	v_add_u32_e32 v183, s10, v183
	v_mul_u32_u24_e32 v41, 0x1600, v183
	v_add_u32_e32 v41, s12, v41
	v_add_u32_e32 v41, v41, v40
	s_lshl_b32 s51, 0xb000, s9
	s_mul_i32 s17, s8, s11
	s_sub_i32 s16, s13, s12
	s_add_i32 s17, s17, s16
	v_add_u32_e32 v42, s17, v41
	v_add_u32_e32 v43, s51, v42
	v_add_u32_e32 v44, s51, v43
	v_add_u32_e32 v45, s51, v44
	s_add_i32 m0, s50, 0x3000
	global_load_lds_dwordx4 v42, s[2:3]
	s_add_i32 m0, s50, 0x3400
	global_load_lds_dwordx4 v43, s[2:3]
	s_add_i32 m0, s50, 0x3800
	global_load_lds_dwordx4 v44, s[2:3]
	s_add_i32 m0, s50, 0x3c00
	global_load_lds_dwordx4 v45, s[2:3]
	s_add_i32 s16, s8, -4
	s_max_i32 s16, s16, 0
	s_mul_i32 s17, s16, s11
	v_add_u32_e32 v42, s17, v41
	v_add_u32_e32 v43, s51, v42
	v_add_u32_e32 v44, s51, v43
	v_add_u32_e32 v45, s51, v44
	s_add_i32 m0, s50, 0x0
	global_load_lds_dwordx4 v42, s[2:3]
	s_add_i32 m0, s50, 0x400
	global_load_lds_dwordx4 v43, s[2:3]
	s_add_i32 m0, s50, 0x800
	global_load_lds_dwordx4 v44, s[2:3]
	s_add_i32 m0, s50, 0xc00
	global_load_lds_dwordx4 v45, s[2:3]
	s_add_i32 s16, s8, -4
	s_max_i32 s16, s16, 0
	s_lshl_b32 s17, s16, 12
	v_add_u32_e32 v58, s17, v46
	global_load_dwordx4 v[82:85], v58, s[4:5]
	global_load_dwordx4 v[86:89], v58, s[4:5] offset:1024
	global_load_dwordx4 v[90:93], v58, s[4:5] offset:2048
	global_load_dwordx4 v[94:97], v58, s[4:5] offset:3072
	s_add_i32 s16, s8, -3
	s_max_i32 s16, s16, 0
	s_mul_i32 s17, s16, s11
	v_add_u32_e32 v42, s17, v41
	v_add_u32_e32 v43, s51, v42
	v_add_u32_e32 v44, s51, v43
	v_add_u32_e32 v45, s51, v44
	s_add_i32 m0, s50, 0x1000
	global_load_lds_dwordx4 v42, s[2:3]
	s_add_i32 m0, s50, 0x1400
	global_load_lds_dwordx4 v43, s[2:3]
	s_add_i32 m0, s50, 0x1800
	global_load_lds_dwordx4 v44, s[2:3]
	s_add_i32 m0, s50, 0x1c00
	global_load_lds_dwordx4 v45, s[2:3]
	s_add_i32 s16, s8, -3
	s_max_i32 s16, s16, 0
	s_lshl_b32 s17, s16, 12
	v_add_u32_e32 v58, s17, v46
	global_load_dwordx4 v[98:101], v58, s[4:5]
	global_load_dwordx4 v[102:105], v58, s[4:5] offset:1024
	global_load_dwordx4 v[106:109], v58, s[4:5] offset:2048
	global_load_dwordx4 v[110:113], v58, s[4:5] offset:3072
	s_add_i32 s16, s8, -2
	s_max_i32 s16, s16, 0
	s_mul_i32 s17, s16, s11
	v_add_u32_e32 v42, s17, v41
	v_add_u32_e32 v43, s51, v42
	v_add_u32_e32 v44, s51, v43
	v_add_u32_e32 v45, s51, v44
	s_add_i32 m0, s50, 0x2000
	global_load_lds_dwordx4 v42, s[2:3]
	s_add_i32 m0, s50, 0x2400
	global_load_lds_dwordx4 v43, s[2:3]
	s_add_i32 m0, s50, 0x2800
	global_load_lds_dwordx4 v44, s[2:3]
	s_add_i32 m0, s50, 0x2c00
	global_load_lds_dwordx4 v45, s[2:3]
	s_add_i32 s16, s8, -2
	s_max_i32 s16, s16, 0
	s_lshl_b32 s17, s16, 12
	v_add_u32_e32 v58, s17, v46
	global_load_dwordx4 v[114:117], v58, s[4:5]
	global_load_dwordx4 v[118:121], v58, s[4:5] offset:1024
	global_load_dwordx4 v[122:125], v58, s[4:5] offset:2048
	global_load_dwordx4 v[126:129], v58, s[4:5] offset:3072
	v_cvt_f32_i32_e32 v51, s24
	v_mul_f32_e32 v51, 0xbf2aaaab, v51
	v_exp_f32_e32 v51, v51
	v_cvt_f32_i32_e32 v52, v54
	v_mul_f32_e32 v51, 0x3fb8aa3b, v51
	v_ldexp_f32 v51, v51, s9
	v_mul_f32_e64 v52, -v51, v52
	v_mul_f32_e32 v18, 0x00000000, v51
	v_mul_f32_e32 v19, 0x3f800000, v51
	v_mul_f32_e32 v20, 0x40000000, v51
	v_mul_f32_e32 v21, 0x40400000, v51
	v_mul_f32_e32 v22, 0x41000000, v51
	v_mul_f32_e32 v23, 0x41100000, v51
	v_mul_f32_e32 v24, 0x41200000, v51
	v_mul_f32_e32 v25, 0x41300000, v51
	v_mul_f32_e32 v26, 0x41800000, v51
	v_mul_f32_e32 v27, 0x41880000, v51
	v_mul_f32_e32 v28, 0x41900000, v51
	v_mul_f32_e32 v29, 0x41980000, v51
	v_mul_f32_e32 v30, 0x41c00000, v51
	v_mul_f32_e32 v31, 0x41c80000, v51
	v_mul_f32_e32 v32, 0x41d00000, v51
	v_mul_f32_e32 v33, 0x41d80000, v51
	v_readfirstlane_b32 s34, v18
	v_readfirstlane_b32 s35, v19
	v_readfirstlane_b32 s36, v20
	v_readfirstlane_b32 s37, v21
	v_readfirstlane_b32 s38, v22
	v_readfirstlane_b32 s39, v23
	v_readfirstlane_b32 s40, v24
	v_readfirstlane_b32 s41, v25
	v_readfirstlane_b32 s42, v26
	v_readfirstlane_b32 s43, v27
	v_readfirstlane_b32 s44, v28
	v_readfirstlane_b32 s45, v29
	v_readfirstlane_b32 s46, v30
	v_readfirstlane_b32 s47, v31
	v_readfirstlane_b32 s48, v32
	v_readfirstlane_b32 s49, v33
	v_add_u32_e32 v55, s15, v54
	v_lshlrev_b32_e32 v62, s14, v57
	v_lshl_add_u32 v62, v48, 3, v62
	v_lshlrev_b32_e32 v63, 4, v57
	v_mov_b32_e32 v49, 0xf149f2ca
	v_mov_b32_e32 v34, 0xf149f2ca
	v_mov_b32_e32 v50, 0
	v_mov_b32_e32 v146, 0
	v_mov_b32_e32 v147, 0
	v_mov_b32_e32 v148, 0
	v_mov_b32_e32 v149, 0
	v_mov_b32_e32 v150, 0
	v_mov_b32_e32 v151, 0
	v_mov_b32_e32 v152, 0
	v_mov_b32_e32 v153, 0
	v_mov_b32_e32 v154, 0
	v_mov_b32_e32 v155, 0
	v_mov_b32_e32 v156, 0
	v_mov_b32_e32 v157, 0
	v_mov_b32_e32 v158, 0
	v_mov_b32_e32 v159, 0
	v_mov_b32_e32 v160, 0
	v_mov_b32_e32 v161, 0
	v_mov_b32_e32 v184, 0
	v_mov_b32_e32 v185, 0
	v_mov_b32_e32 v186, 0
	v_mov_b32_e32 v187, 0
	v_mov_b32_e32 v188, 0
	v_mov_b32_e32 v189, 0
	v_mov_b32_e32 v190, 0
	v_mov_b32_e32 v191, 0
	v_mov_b32_e32 v192, 0
	v_mov_b32_e32 v193, 0
	v_mov_b32_e32 v194, 0
	v_mov_b32_e32 v195, 0
	v_mov_b32_e32 v196, 0
	v_mov_b32_e32 v197, 0
	v_mov_b32_e32 v198, 0
	v_mov_b32_e32 v199, 0
	s_waitcnt vmcnt(24)
	ds_read_b128 v[130:133], v35 offset:12288
	ds_read_b128 v[134:137], v36 offset:12288
	ds_read_b128 v[138:141], v37 offset:12288
	ds_read_b128 v[142:145], v38 offset:12288
	s_waitcnt lgkmcnt(0)
	s_cmp_lt_i32 s8, 4
	s_cbranch_scc1 .Lband_s0a
	s_waitcnt vmcnt(20)
	ds_read_b128 v[2:5], v35 offset:0
	ds_read_b128 v[6:9], v36 offset:0
	ds_read_b128 v[10:13], v37 offset:0
	ds_read_b128 v[14:17], v38 offset:0
	s_waitcnt lgkmcnt(0)
	v_mfma_f32_32x32x16_bf16 v[18:33], v[2:5], v[130:133], 0
	v_mfma_f32_32x32x16_bf16 v[18:33], v[6:9], v[134:137], v[18:33]
	v_mfma_f32_32x32x16_bf16 v[18:33], v[10:13], v[138:141], v[18:33]
	v_mfma_f32_32x32x16_bf16 v[18:33], v[14:17], v[142:145], v[18:33]
.Lband_s0a:
	s_add_i32 s16, s8, -1
	s_max_i32 s16, s16, 0
	s_mul_i32 s17, s16, s11
	v_add_u32_e32 v42, s17, v41
	v_add_u32_e32 v43, s51, v42
	v_add_u32_e32 v44, s51, v43
	v_add_u32_e32 v45, s51, v44
	s_add_i32 m0, s50, 0x0
	global_load_lds_dwordx4 v42, s[2:3]
	s_add_i32 m0, s50, 0x400
	global_load_lds_dwordx4 v43, s[2:3]
	s_add_i32 m0, s50, 0x800
	global_load_lds_dwordx4 v44, s[2:3]
	s_add_i32 m0, s50, 0xc00
	global_load_lds_dwordx4 v45, s[2:3]
	s_cmp_lt_i32 s8, 4
	s_cbranch_scc1 .Lband_s0b
	v_fmamk_f32 v53, v51, 0xc3000000, v52
	s_nop 7
	s_nop 4
	v_pk_fma_f32 v[18:19], v[18:19], v[66:67], s[34:35] op_sel_hi:[1,0,1]
	v_pk_fma_f32 v[20:21], v[20:21], v[66:67], s[36:37] op_sel_hi:[1,0,1]
	v_pk_fma_f32 v[22:23], v[22:23], v[66:67], s[38:39] op_sel_hi:[1,0,1]
	v_pk_fma_f32 v[24:25], v[24:25], v[66:67], s[40:41] op_sel_hi:[1,0,1]
	v_pk_fma_f32 v[26:27], v[26:27], v[66:67], s[42:43] op_sel_hi:[1,0,1]
	v_pk_fma_f32 v[28:29], v[28:29], v[66:67], s[44:45] op_sel_hi:[1,0,1]
	v_pk_fma_f32 v[30:31], v[30:31], v[66:67], s[46:47] op_sel_hi:[1,0,1]
	v_pk_fma_f32 v[32:33], v[32:33], v[66:67], s[48:49] op_sel_hi:[1,0,1]
	v_cmp_ge_i32_e64 s[16:17], 0, v55
	v_cmp_ge_i32_e64 s[22:23], 1, v55
	v_cmp_ge_i32_e64 s[24:25], 2, v55
	v_cmp_ge_i32_e64 s[28:29], 3, v55
	v_cmp_ge_i32_e32 vcc, 8, v55
	v_cndmask_b32_e64 v18, v67, v18, s[16:17]
	v_cndmask_b32_e64 v19, v67, v19, s[22:23]
	v_cndmask_b32_e64 v20, v67, v20, s[24:25]
	v_cndmask_b32_e64 v21, v67, v21, s[28:29]
	v_cndmask_b32_e64 v22, v67, v22, vcc
	v_cmp_ge_i32_e64 s[16:17], 9, v55
	v_cmp_ge_i32_e64 s[22:23], 10, v55
	v_cmp_ge_i32_e64 s[24:25], 11, v55
	v_cmp_ge_i32_e64 s[28:29], 16, v55
	v_cmp_ge_i32_e32 vcc, 17, v55
	v_cndmask_b32_e64 v23, v67, v23, s[16:17]
	v_cndmask_b32_e64 v24, v67, v24, s[22:23]
	v_cndmask_b32_e64 v25, v67, v25, s[24:25]
	v_cndmask_b32_e64 v26, v67, v26, s[28:29]
	v_cndmask_b32_e64 v27, v67, v27, vcc
	v_cmp_ge_i32_e64 s[16:17], 18, v55
	v_cmp_ge_i32_e64 s[22:23], 19, v55
	v_cmp_ge_i32_e64 s[24:25], 24, v55
	v_cmp_ge_i32_e64 s[28:29], 25, v55
	v_cmp_ge_i32_e32 vcc, 26, v55
	v_cndmask_b32_e64 v28, v67, v28, s[16:17]
	v_cndmask_b32_e64 v29, v67, v29, s[22:23]
	v_cndmask_b32_e64 v30, v67, v30, s[24:25]
	v_cndmask_b32_e64 v31, v67, v31, s[28:29]
	v_cndmask_b32_e64 v32, v67, v32, vcc
	v_cmp_ge_i32_e64 s[16:17], 27, v55
	s_nop 1
	v_cndmask_b32_e64 v33, v67, v33, s[16:17]
	v_max3_f32 v183, v18, v19, v20
	v_max3_f32 v64, v21, v22, v23
	v_max3_f32 v60, v24, v25, v26
	v_max3_f32 v61, v27, v28, v29
	v_max3_f32 v68, v30, v31, v32
	v_max3_f32 v183, v183, v64, v60
	v_max3_f32 v61, v61, v68, v33
	v_max_f32_e32 v183, v183, v61
	v_add_f32_e32 v183, v183, v53
	v_mov_b32_e32 v64, v183
	s_nop 1
	v_permlane32_swap_b32_e32 v64, v183
	v_max_f32_e32 v183, v183, v64
	v_cmp_lt_f32_e32 vcc, v34, v183
	s_cbranch_vccz .Lband_keep0
	v_max_f32_e32 v64, v49, v183
	v_sub_f32_e32 v60, v49, v64
	v_exp_f32_e32 v60, v60
	v_mov_b32_e32 v49, v64
	v_add_f32_e32 v34, 0x41a00000, v64
	v_mul_f32_e32 v50, v50, v60
	v_pk_mul_f32 v[146:147], v[146:147], v[60:61] op_sel_hi:[1,0]
	v_pk_mul_f32 v[148:149], v[148:149], v[60:61] op_sel_hi:[1,0]
	v_pk_mul_f32 v[150:151], v[150:151], v[60:61] op_sel_hi:[1,0]
	v_pk_mul_f32 v[152:153], v[152:153], v[60:61] op_sel_hi:[1,0]
	v_pk_mul_f32 v[154:155], v[154:155], v[60:61] op_sel_hi:[1,0]
	v_pk_mul_f32 v[156:157], v[156:157], v[60:61] op_sel_hi:[1,0]
	v_pk_mul_f32 v[158:159], v[158:159], v[60:61] op_sel_hi:[1,0]
	v_pk_mul_f32 v[160:161], v[160:161], v[60:61] op_sel_hi:[1,0]
	v_pk_mul_f32 v[184:185], v[184:185], v[60:61] op_sel_hi:[1,0]
	v_pk_mul_f32 v[186:187], v[186:187], v[60:61] op_sel_hi:[1,0]
	v_pk_mul_f32 v[188:189], v[188:189], v[60:61] op_sel_hi:[1,0]
	v_pk_mul_f32 v[190:191], v[190:191], v[60:61] op_sel_hi:[1,0]
	v_pk_mul_f32 v[192:193], v[192:193], v[60:61] op_sel_hi:[1,0]
	v_pk_mul_f32 v[194:195], v[194:195], v[60:61] op_sel_hi:[1,0]
	v_pk_mul_f32 v[196:197], v[196:197], v[60:61] op_sel_hi:[1,0]
	v_pk_mul_f32 v[198:199], v[198:199], v[60:61] op_sel_hi:[1,0]
.Lband_keep0:
	v_sub_f32_e32 v68, v53, v49
	v_pk_add_f32 v[18:19], v[18:19], v[68:69] op_sel_hi:[1,0]
	v_exp_f32_e32 v18, v18
	v_exp_f32_e32 v19, v19
	v_pk_add_f32 v[20:21], v[20:21], v[68:69] op_sel_hi:[1,0]
	v_exp_f32_e32 v20, v20
	v_exp_f32_e32 v21, v21
	v_pk_add_f32 v[22:23], v[22:23], v[68:69] op_sel_hi:[1,0]
	v_exp_f32_e32 v22, v22
	v_exp_f32_e32 v23, v23
	v_pk_add_f32 v[24:25], v[24:25], v[68:69] op_sel_hi:[1,0]
	v_exp_f32_e32 v24, v24
	v_exp_f32_e32 v25, v25
	v_pk_add_f32 v[26:27], v[26:27], v[68:69] op_sel_hi:[1,0]
	v_exp_f32_e32 v26, v26
	v_exp_f32_e32 v27, v27
	v_pk_add_f32 v[28:29], v[28:29], v[68:69] op_sel_hi:[1,0]
	v_exp_f32_e32 v28, v28
	v_exp_f32_e32 v29, v29
	v_pk_add_f32 v[30:31], v[30:31], v[68:69] op_sel_hi:[1,0]
	v_exp_f32_e32 v30, v30
	v_exp_f32_e32 v31, v31
	v_pk_add_f32 v[32:33], v[32:33], v[68:69] op_sel_hi:[1,0]
	v_exp_f32_e32 v32, v32
	v_exp_f32_e32 v33, v33
	v_pk_add_f32 v[68:69], v[18:19], v[20:21]
	v_pk_add_f32 v[60:61], v[22:23], v[24:25]
	v_pk_add_f32 v[68:69], v[68:69], v[26:27]
	v_pk_add_f32 v[60:61], v[60:61], v[28:29]
	v_pk_add_f32 v[68:69], v[68:69], v[30:31]
	v_pk_add_f32 v[60:61], v[60:61], v[32:33]
	v_pk_add_f32 v[68:69], v[68:69], v[60:61]
	v_add_f32_e32 v183, v68, v69
	v_add_f32_e32 v50, v50, v183
	v_cvt_pk_bf16_f32 v18, v18, v19
	v_cvt_pk_bf16_f32 v19, v20, v21
	v_cvt_pk_bf16_f32 v20, v22, v23
	v_cvt_pk_bf16_f32 v21, v24, v25
	v_cvt_pk_bf16_f32 v22, v26, v27
	v_cvt_pk_bf16_f32 v23, v28, v29
	v_cvt_pk_bf16_f32 v24, v30, v31
	v_cvt_pk_bf16_f32 v25, v32, v33
	s_waitcnt vmcnt(20)
	s_nop 1
	v_mfma_f32_32x32x16_bf16 v[146:161], v[82:85], v[18:21], v[146:161]
	v_mfma_f32_32x32x16_bf16 v[184:199], v[90:93], v[18:21], v[184:199]
	v_mfma_f32_32x32x16_bf16 v[146:161], v[86:89], v[22:25], v[146:161]
	v_mfma_f32_32x32x16_bf16 v[184:199], v[94:97], v[22:25], v[184:199]
.Lband_s0b:
	s_add_i32 s16, s8, -1
	s_max_i32 s16, s16, 0
	s_lshl_b32 s17, s16, 12
	v_add_u32_e32 v58, s17, v46
	global_load_dwordx4 v[82:85], v58, s[4:5]
	global_load_dwordx4 v[86:89], v58, s[4:5] offset:1024
	global_load_dwordx4 v[90:93], v58, s[4:5] offset:2048
	global_load_dwordx4 v[94:97], v58, s[4:5] offset:3072
	s_cmp_lt_i32 s8, 3
	s_cbranch_scc1 .Lband_s1a
	s_waitcnt vmcnt(20)
	ds_read_b128 v[2:5], v35 offset:4096
	ds_read_b128 v[6:9], v36 offset:4096
	ds_read_b128 v[10:13], v37 offset:4096
	ds_read_b128 v[14:17], v38 offset:4096
	s_waitcnt lgkmcnt(0)
	v_mfma_f32_32x32x16_bf16 v[18:33], v[2:5], v[130:133], 0
	v_mfma_f32_32x32x16_bf16 v[18:33], v[6:9], v[134:137], v[18:33]
	v_mfma_f32_32x32x16_bf16 v[18:33], v[10:13], v[138:141], v[18:33]
	v_mfma_f32_32x32x16_bf16 v[18:33], v[14:17], v[142:145], v[18:33]
.Lband_s1a:
	s_add_i32 s16, s8, 0
	s_max_i32 s16, s16, 0
	s_mul_i32 s17, s16, s11
	v_add_u32_e32 v42, s17, v41
	v_add_u32_e32 v43, s51, v42
	v_add_u32_e32 v44, s51, v43
	v_add_u32_e32 v45, s51, v44
	s_add_i32 m0, s50, 0x1000
	global_load_lds_dwordx4 v42, s[2:3]
	s_add_i32 m0, s50, 0x1400
	global_load_lds_dwordx4 v43, s[2:3]
	s_add_i32 m0, s50, 0x1800
	global_load_lds_dwordx4 v44, s[2:3]
	s_add_i32 m0, s50, 0x1c00
	global_load_lds_dwordx4 v45, s[2:3]
	s_cmp_lt_i32 s8, 3
	s_cbranch_scc1 .Lband_s1b
	v_fmamk_f32 v53, v51, 0xc2c00000, v52
	s_nop 7
	s_nop 4
	v_pk_fma_f32 v[18:19], v[18:19], v[66:67], s[34:35] op_sel_hi:[1,0,1]
	v_pk_fma_f32 v[20:21], v[20:21], v[66:67], s[36:37] op_sel_hi:[1,0,1]
	v_pk_fma_f32 v[22:23], v[22:23], v[66:67], s[38:39] op_sel_hi:[1,0,1]
	v_pk_fma_f32 v[24:25], v[24:25], v[66:67], s[40:41] op_sel_hi:[1,0,1]
	v_pk_fma_f32 v[26:27], v[26:27], v[66:67], s[42:43] op_sel_hi:[1,0,1]
	v_pk_fma_f32 v[28:29], v[28:29], v[66:67], s[44:45] op_sel_hi:[1,0,1]
	v_pk_fma_f32 v[30:31], v[30:31], v[66:67], s[46:47] op_sel_hi:[1,0,1]
	v_pk_fma_f32 v[32:33], v[32:33], v[66:67], s[48:49] op_sel_hi:[1,0,1]
	v_max3_f32 v183, v18, v19, v20
	v_max3_f32 v64, v21, v22, v23
	v_max3_f32 v60, v24, v25, v26
	v_max3_f32 v61, v27, v28, v29
	v_max3_f32 v68, v30, v31, v32
	v_max3_f32 v183, v183, v64, v60
	v_max3_f32 v61, v61, v68, v33
	v_max_f32_e32 v183, v183, v61
	v_add_f32_e32 v183, v183, v53
	v_mov_b32_e32 v64, v183
	s_nop 1
	v_permlane32_swap_b32_e32 v64, v183
	v_max_f32_e32 v183, v183, v64
	v_cmp_lt_f32_e32 vcc, v34, v183
	s_cbranch_vccz .Lband_keep1
	v_max_f32_e32 v64, v49, v183
	v_sub_f32_e32 v60, v49, v64
	v_exp_f32_e32 v60, v60
	v_mov_b32_e32 v49, v64
	v_add_f32_e32 v34, 0x41a00000, v64
	v_mul_f32_e32 v50, v50, v60
	v_pk_mul_f32 v[146:147], v[146:147], v[60:61] op_sel_hi:[1,0]
	v_pk_mul_f32 v[148:149], v[148:149], v[60:61] op_sel_hi:[1,0]
	v_pk_mul_f32 v[150:151], v[150:151], v[60:61] op_sel_hi:[1,0]
	v_pk_mul_f32 v[152:153], v[152:153], v[60:61] op_sel_hi:[1,0]
	v_pk_mul_f32 v[154:155], v[154:155], v[60:61] op_sel_hi:[1,0]
	v_pk_mul_f32 v[156:157], v[156:157], v[60:61] op_sel_hi:[1,0]
	v_pk_mul_f32 v[158:159], v[158:159], v[60:61] op_sel_hi:[1,0]
	v_pk_mul_f32 v[160:161], v[160:161], v[60:61] op_sel_hi:[1,0]
	v_pk_mul_f32 v[184:185], v[184:185], v[60:61] op_sel_hi:[1,0]
	v_pk_mul_f32 v[186:187], v[186:187], v[60:61] op_sel_hi:[1,0]
	v_pk_mul_f32 v[188:189], v[188:189], v[60:61] op_sel_hi:[1,0]
	v_pk_mul_f32 v[190:191], v[190:191], v[60:61] op_sel_hi:[1,0]
	v_pk_mul_f32 v[192:193], v[192:193], v[60:61] op_sel_hi:[1,0]
	v_pk_mul_f32 v[194:195], v[194:195], v[60:61] op_sel_hi:[1,0]
	v_pk_mul_f32 v[196:197], v[196:197], v[60:61] op_sel_hi:[1,0]
	v_pk_mul_f32 v[198:199], v[198:199], v[60:61] op_sel_hi:[1,0]
.Lband_keep1:
	v_sub_f32_e32 v68, v53, v49
	v_pk_add_f32 v[18:19], v[18:19], v[68:69] op_sel_hi:[1,0]
	v_exp_f32_e32 v18, v18
	v_exp_f32_e32 v19, v19
	v_pk_add_f32 v[20:21], v[20:21], v[68:69] op_sel_hi:[1,0]
	v_exp_f32_e32 v20, v20
	v_exp_f32_e32 v21, v21
	v_pk_add_f32 v[22:23], v[22:23], v[68:69] op_sel_hi:[1,0]
	v_exp_f32_e32 v22, v22
	v_exp_f32_e32 v23, v23
	v_pk_add_f32 v[24:25], v[24:25], v[68:69] op_sel_hi:[1,0]
	v_exp_f32_e32 v24, v24
	v_exp_f32_e32 v25, v25
	v_pk_add_f32 v[26:27], v[26:27], v[68:69] op_sel_hi:[1,0]
	v_exp_f32_e32 v26, v26
	v_exp_f32_e32 v27, v27
	v_pk_add_f32 v[28:29], v[28:29], v[68:69] op_sel_hi:[1,0]
	v_exp_f32_e32 v28, v28
	v_exp_f32_e32 v29, v29
	v_pk_add_f32 v[30:31], v[30:31], v[68:69] op_sel_hi:[1,0]
	v_exp_f32_e32 v30, v30
	v_exp_f32_e32 v31, v31
	v_pk_add_f32 v[32:33], v[32:33], v[68:69] op_sel_hi:[1,0]
	v_exp_f32_e32 v32, v32
	v_exp_f32_e32 v33, v33
	v_pk_add_f32 v[68:69], v[18:19], v[20:21]
	v_pk_add_f32 v[60:61], v[22:23], v[24:25]
	v_pk_add_f32 v[68:69], v[68:69], v[26:27]
	v_pk_add_f32 v[60:61], v[60:61], v[28:29]
	v_pk_add_f32 v[68:69], v[68:69], v[30:31]
	v_pk_add_f32 v[60:61], v[60:61], v[32:33]
	v_pk_add_f32 v[68:69], v[68:69], v[60:61]
	v_add_f32_e32 v183, v68, v69
	v_add_f32_e32 v50, v50, v183
	v_cvt_pk_bf16_f32 v18, v18, v19
	v_cvt_pk_bf16_f32 v19, v20, v21
	v_cvt_pk_bf16_f32 v20, v22, v23
	v_cvt_pk_bf16_f32 v21, v24, v25
	v_cvt_pk_bf16_f32 v22, v26, v27
	v_cvt_pk_bf16_f32 v23, v28, v29
	v_cvt_pk_bf16_f32 v24, v30, v31
	v_cvt_pk_bf16_f32 v25, v32, v33
	s_waitcnt vmcnt(20)
	s_nop 1
	v_mfma_f32_32x32x16_bf16 v[146:161], v[98:101], v[18:21], v[146:161]
	v_mfma_f32_32x32x16_bf16 v[184:199], v[106:109], v[18:21], v[184:199]
	v_mfma_f32_32x32x16_bf16 v[146:161], v[102:105], v[22:25], v[146:161]
	v_mfma_f32_32x32x16_bf16 v[184:199], v[110:113], v[22:25], v[184:199]
.Lband_s1b:
	s_add_i32 s16, s8, 0
	s_max_i32 s16, s16, 0
	s_lshl_b32 s17, s16, 12
	v_add_u32_e32 v58, s17, v46
	global_load_dwordx4 v[98:101], v58, s[4:5]
	global_load_dwordx4 v[102:105], v58, s[4:5] offset:1024
	global_load_dwordx4 v[106:109], v58, s[4:5] offset:2048
	global_load_dwordx4 v[110:113], v58, s[4:5] offset:3072
	s_cmp_lt_i32 s8, 2
	s_cbranch_scc1 .Lband_s2a
	s_waitcnt vmcnt(20)
	ds_read_b128 v[2:5], v35 offset:8192
	ds_read_b128 v[6:9], v36 offset:8192
	ds_read_b128 v[10:13], v37 offset:8192
	ds_read_b128 v[14:17], v38 offset:8192
	s_waitcnt lgkmcnt(0)
	v_mfma_f32_32x32x16_bf16 v[18:33], v[2:5], v[130:133], 0
	v_mfma_f32_32x32x16_bf16 v[18:33], v[6:9], v[134:137], v[18:33]
	v_mfma_f32_32x32x16_bf16 v[18:33], v[10:13], v[138:141], v[18:33]
	v_mfma_f32_32x32x16_bf16 v[18:33], v[14:17], v[142:145], v[18:33]
.Lband_s2a:
	s_cmp_lt_i32 s8, 2
	s_cbranch_scc1 .Lband_s2b
	v_fmamk_f32 v53, v51, 0xc2800000, v52
	s_nop 7
	s_nop 4
	v_pk_fma_f32 v[18:19], v[18:19], v[66:67], s[34:35] op_sel_hi:[1,0,1]
	v_pk_fma_f32 v[20:21], v[20:21], v[66:67], s[36:37] op_sel_hi:[1,0,1]
	v_pk_fma_f32 v[22:23], v[22:23], v[66:67], s[38:39] op_sel_hi:[1,0,1]
	v_pk_fma_f32 v[24:25], v[24:25], v[66:67], s[40:41] op_sel_hi:[1,0,1]
	v_pk_fma_f32 v[26:27], v[26:27], v[66:67], s[42:43] op_sel_hi:[1,0,1]
	v_pk_fma_f32 v[28:29], v[28:29], v[66:67], s[44:45] op_sel_hi:[1,0,1]
	v_pk_fma_f32 v[30:31], v[30:31], v[66:67], s[46:47] op_sel_hi:[1,0,1]
	v_pk_fma_f32 v[32:33], v[32:33], v[66:67], s[48:49] op_sel_hi:[1,0,1]
	v_max3_f32 v183, v18, v19, v20
	v_max3_f32 v64, v21, v22, v23
	v_max3_f32 v60, v24, v25, v26
	v_max3_f32 v61, v27, v28, v29
	v_max3_f32 v68, v30, v31, v32
	v_max3_f32 v183, v183, v64, v60
	v_max3_f32 v61, v61, v68, v33
	v_max_f32_e32 v183, v183, v61
	v_add_f32_e32 v183, v183, v53
	v_mov_b32_e32 v64, v183
	s_nop 1
	v_permlane32_swap_b32_e32 v64, v183
	v_max_f32_e32 v183, v183, v64
	v_cmp_lt_f32_e32 vcc, v34, v183
	s_cbranch_vccz .Lband_keep2
	v_max_f32_e32 v64, v49, v183
	v_sub_f32_e32 v60, v49, v64
	v_exp_f32_e32 v60, v60
	v_mov_b32_e32 v49, v64
	v_add_f32_e32 v34, 0x41a00000, v64
	v_mul_f32_e32 v50, v50, v60
	v_pk_mul_f32 v[146:147], v[146:147], v[60:61] op_sel_hi:[1,0]
	v_pk_mul_f32 v[148:149], v[148:149], v[60:61] op_sel_hi:[1,0]
	v_pk_mul_f32 v[150:151], v[150:151], v[60:61] op_sel_hi:[1,0]
	v_pk_mul_f32 v[152:153], v[152:153], v[60:61] op_sel_hi:[1,0]
	v_pk_mul_f32 v[154:155], v[154:155], v[60:61] op_sel_hi:[1,0]
	v_pk_mul_f32 v[156:157], v[156:157], v[60:61] op_sel_hi:[1,0]
	v_pk_mul_f32 v[158:159], v[158:159], v[60:61] op_sel_hi:[1,0]
	v_pk_mul_f32 v[160:161], v[160:161], v[60:61] op_sel_hi:[1,0]
	v_pk_mul_f32 v[184:185], v[184:185], v[60:61] op_sel_hi:[1,0]
	v_pk_mul_f32 v[186:187], v[186:187], v[60:61] op_sel_hi:[1,0]
	v_pk_mul_f32 v[188:189], v[188:189], v[60:61] op_sel_hi:[1,0]
	v_pk_mul_f32 v[190:191], v[190:191], v[60:61] op_sel_hi:[1,0]
	v_pk_mul_f32 v[192:193], v[192:193], v[60:61] op_sel_hi:[1,0]
	v_pk_mul_f32 v[194:195], v[194:195], v[60:61] op_sel_hi:[1,0]
	v_pk_mul_f32 v[196:197], v[196:197], v[60:61] op_sel_hi:[1,0]
	v_pk_mul_f32 v[198:199], v[198:199], v[60:61] op_sel_hi:[1,0]
.Lband_keep2:
	v_sub_f32_e32 v68, v53, v49
	v_pk_add_f32 v[18:19], v[18:19], v[68:69] op_sel_hi:[1,0]
	v_exp_f32_e32 v18, v18
	v_exp_f32_e32 v19, v19
	v_pk_add_f32 v[20:21], v[20:21], v[68:69] op_sel_hi:[1,0]
	v_exp_f32_e32 v20, v20
	v_exp_f32_e32 v21, v21
	v_pk_add_f32 v[22:23], v[22:23], v[68:69] op_sel_hi:[1,0]
	v_exp_f32_e32 v22, v22
	v_exp_f32_e32 v23, v23
	v_pk_add_f32 v[24:25], v[24:25], v[68:69] op_sel_hi:[1,0]
	v_exp_f32_e32 v24, v24
	v_exp_f32_e32 v25, v25
	v_pk_add_f32 v[26:27], v[26:27], v[68:69] op_sel_hi:[1,0]
	v_exp_f32_e32 v26, v26
	v_exp_f32_e32 v27, v27
	v_pk_add_f32 v[28:29], v[28:29], v[68:69] op_sel_hi:[1,0]
	v_exp_f32_e32 v28, v28
	v_exp_f32_e32 v29, v29
	v_pk_add_f32 v[30:31], v[30:31], v[68:69] op_sel_hi:[1,0]
	v_exp_f32_e32 v30, v30
	v_exp_f32_e32 v31, v31
	v_pk_add_f32 v[32:33], v[32:33], v[68:69] op_sel_hi:[1,0]
	v_exp_f32_e32 v32, v32
	v_exp_f32_e32 v33, v33
	v_pk_add_f32 v[68:69], v[18:19], v[20:21]
	v_pk_add_f32 v[60:61], v[22:23], v[24:25]
	v_pk_add_f32 v[68:69], v[68:69], v[26:27]
	v_pk_add_f32 v[60:61], v[60:61], v[28:29]
	v_pk_add_f32 v[68:69], v[68:69], v[30:31]
	v_pk_add_f32 v[60:61], v[60:61], v[32:33]
	v_pk_add_f32 v[68:69], v[68:69], v[60:61]
	v_add_f32_e32 v183, v68, v69
	v_add_f32_e32 v50, v50, v183
	v_cvt_pk_bf16_f32 v18, v18, v19
	v_cvt_pk_bf16_f32 v19, v20, v21
	v_cvt_pk_bf16_f32 v20, v22, v23
	v_cvt_pk_bf16_f32 v21, v24, v25
	v_cvt_pk_bf16_f32 v22, v26, v27
	v_cvt_pk_bf16_f32 v23, v28, v29
	v_cvt_pk_bf16_f32 v24, v30, v31
	v_cvt_pk_bf16_f32 v25, v32, v33
	s_waitcnt vmcnt(16)
	s_nop 1
	v_mfma_f32_32x32x16_bf16 v[146:161], v[114:117], v[18:21], v[146:161]
	v_mfma_f32_32x32x16_bf16 v[184:199], v[122:125], v[18:21], v[184:199]
	v_mfma_f32_32x32x16_bf16 v[146:161], v[118:121], v[22:25], v[146:161]
	v_mfma_f32_32x32x16_bf16 v[184:199], v[126:129], v[22:25], v[184:199]
.Lband_s2b:
	s_cmp_lt_i32 s8, 1
	s_cbranch_scc1 .Lband_s3a
	s_waitcnt vmcnt(12)
	ds_read_b128 v[2:5], v35 offset:0
	ds_read_b128 v[6:9], v36 offset:0
	ds_read_b128 v[10:13], v37 offset:0
	ds_read_b128 v[14:17], v38 offset:0
	s_waitcnt lgkmcnt(0)
	v_mfma_f32_32x32x16_bf16 v[18:33], v[2:5], v[130:133], 0
	v_mfma_f32_32x32x16_bf16 v[18:33], v[6:9], v[134:137], v[18:33]
	v_mfma_f32_32x32x16_bf16 v[18:33], v[10:13], v[138:141], v[18:33]
	v_mfma_f32_32x32x16_bf16 v[18:33], v[14:17], v[142:145], v[18:33]
.Lband_s3a:
	s_cmp_lt_i32 s8, 1
	s_cbranch_scc1 .Lband_s3b
	v_fmamk_f32 v53, v51, 0xc2000000, v52
	s_nop 7
	s_nop 4
	v_pk_fma_f32 v[18:19], v[18:19], v[66:67], s[34:35] op_sel_hi:[1,0,1]
	v_pk_fma_f32 v[20:21], v[20:21], v[66:67], s[36:37] op_sel_hi:[1,0,1]
	v_pk_fma_f32 v[22:23], v[22:23], v[66:67], s[38:39] op_sel_hi:[1,0,1]
	v_pk_fma_f32 v[24:25], v[24:25], v[66:67], s[40:41] op_sel_hi:[1,0,1]
	v_pk_fma_f32 v[26:27], v[26:27], v[66:67], s[42:43] op_sel_hi:[1,0,1]
	v_pk_fma_f32 v[28:29], v[28:29], v[66:67], s[44:45] op_sel_hi:[1,0,1]
	v_pk_fma_f32 v[30:31], v[30:31], v[66:67], s[46:47] op_sel_hi:[1,0,1]
	v_pk_fma_f32 v[32:33], v[32:33], v[66:67], s[48:49] op_sel_hi:[1,0,1]
	v_max3_f32 v183, v18, v19, v20
	v_max3_f32 v64, v21, v22, v23
	v_max3_f32 v60, v24, v25, v26
	v_max3_f32 v61, v27, v28, v29
	v_max3_f32 v68, v30, v31, v32
	v_max3_f32 v183, v183, v64, v60
	v_max3_f32 v61, v61, v68, v33
	v_max_f32_e32 v183, v183, v61
	v_add_f32_e32 v183, v183, v53
	v_mov_b32_e32 v64, v183
	s_nop 1
	v_permlane32_swap_b32_e32 v64, v183
	v_max_f32_e32 v183, v183, v64
	v_cmp_lt_f32_e32 vcc, v34, v183
	s_cbranch_vccz .Lband_keep3
	v_max_f32_e32 v64, v49, v183
	v_sub_f32_e32 v60, v49, v64
	v_exp_f32_e32 v60, v60
	v_mov_b32_e32 v49, v64
	v_add_f32_e32 v34, 0x41a00000, v64
	v_mul_f32_e32 v50, v50, v60
	v_pk_mul_f32 v[146:147], v[146:147], v[60:61] op_sel_hi:[1,0]
	v_pk_mul_f32 v[148:149], v[148:149], v[60:61] op_sel_hi:[1,0]
	v_pk_mul_f32 v[150:151], v[150:151], v[60:61] op_sel_hi:[1,0]
	v_pk_mul_f32 v[152:153], v[152:153], v[60:61] op_sel_hi:[1,0]
	v_pk_mul_f32 v[154:155], v[154:155], v[60:61] op_sel_hi:[1,0]
	v_pk_mul_f32 v[156:157], v[156:157], v[60:61] op_sel_hi:[1,0]
	v_pk_mul_f32 v[158:159], v[158:159], v[60:61] op_sel_hi:[1,0]
	v_pk_mul_f32 v[160:161], v[160:161], v[60:61] op_sel_hi:[1,0]
	v_pk_mul_f32 v[184:185], v[184:185], v[60:61] op_sel_hi:[1,0]
	v_pk_mul_f32 v[186:187], v[186:187], v[60:61] op_sel_hi:[1,0]
	v_pk_mul_f32 v[188:189], v[188:189], v[60:61] op_sel_hi:[1,0]
	v_pk_mul_f32 v[190:191], v[190:191], v[60:61] op_sel_hi:[1,0]
	v_pk_mul_f32 v[192:193], v[192:193], v[60:61] op_sel_hi:[1,0]
	v_pk_mul_f32 v[194:195], v[194:195], v[60:61] op_sel_hi:[1,0]
	v_pk_mul_f32 v[196:197], v[196:197], v[60:61] op_sel_hi:[1,0]
	v_pk_mul_f32 v[198:199], v[198:199], v[60:61] op_sel_hi:[1,0]
.Lband_keep3:
	v_sub_f32_e32 v68, v53, v49
	v_pk_add_f32 v[18:19], v[18:19], v[68:69] op_sel_hi:[1,0]
	v_exp_f32_e32 v18, v18
	v_exp_f32_e32 v19, v19
	v_pk_add_f32 v[20:21], v[20:21], v[68:69] op_sel_hi:[1,0]
	v_exp_f32_e32 v20, v20
	v_exp_f32_e32 v21, v21
	v_pk_add_f32 v[22:23], v[22:23], v[68:69] op_sel_hi:[1,0]
	v_exp_f32_e32 v22, v22
	v_exp_f32_e32 v23, v23
	v_pk_add_f32 v[24:25], v[24:25], v[68:69] op_sel_hi:[1,0]
	v_exp_f32_e32 v24, v24
	v_exp_f32_e32 v25, v25
	v_pk_add_f32 v[26:27], v[26:27], v[68:69] op_sel_hi:[1,0]
	v_exp_f32_e32 v26, v26
	v_exp_f32_e32 v27, v27
	v_pk_add_f32 v[28:29], v[28:29], v[68:69] op_sel_hi:[1,0]
	v_exp_f32_e32 v28, v28
	v_exp_f32_e32 v29, v29
	v_pk_add_f32 v[30:31], v[30:31], v[68:69] op_sel_hi:[1,0]
	v_exp_f32_e32 v30, v30
	v_exp_f32_e32 v31, v31
	v_pk_add_f32 v[32:33], v[32:33], v[68:69] op_sel_hi:[1,0]
	v_exp_f32_e32 v32, v32
	v_exp_f32_e32 v33, v33
	v_pk_add_f32 v[68:69], v[18:19], v[20:21]
	v_pk_add_f32 v[60:61], v[22:23], v[24:25]
	v_pk_add_f32 v[68:69], v[68:69], v[26:27]
	v_pk_add_f32 v[60:61], v[60:61], v[28:29]
	v_pk_add_f32 v[68:69], v[68:69], v[30:31]
	v_pk_add_f32 v[60:61], v[60:61], v[32:33]
	v_pk_add_f32 v[68:69], v[68:69], v[60:61]
	v_add_f32_e32 v183, v68, v69
	v_add_f32_e32 v50, v50, v183
	v_cvt_pk_bf16_f32 v18, v18, v19
	v_cvt_pk_bf16_f32 v19, v20, v21
	v_cvt_pk_bf16_f32 v20, v22, v23
	v_cvt_pk_bf16_f32 v21, v24, v25
	v_cvt_pk_bf16_f32 v22, v26, v27
	v_cvt_pk_bf16_f32 v23, v28, v29
	v_cvt_pk_bf16_f32 v24, v30, v31
	v_cvt_pk_bf16_f32 v25, v32, v33
	s_waitcnt vmcnt(8)
	s_nop 1
	v_mfma_f32_32x32x16_bf16 v[146:161], v[82:85], v[18:21], v[146:161]
	v_mfma_f32_32x32x16_bf16 v[184:199], v[90:93], v[18:21], v[184:199]
	v_mfma_f32_32x32x16_bf16 v[146:161], v[86:89], v[22:25], v[146:161]
	v_mfma_f32_32x32x16_bf16 v[184:199], v[94:97], v[22:25], v[184:199]
.Lband_s3b:
	s_waitcnt vmcnt(4)
	ds_read_b128 v[2:5], v35 offset:4096
	ds_read_b128 v[6:9], v36 offset:4096
	ds_read_b128 v[10:13], v37 offset:4096
	ds_read_b128 v[14:17], v38 offset:4096
	s_waitcnt lgkmcnt(0)
	v_mfma_f32_32x32x16_bf16 v[18:33], v[2:5], v[130:133], 0
	v_mfma_f32_32x32x16_bf16 v[18:33], v[6:9], v[134:137], v[18:33]
	v_mfma_f32_32x32x16_bf16 v[18:33], v[10:13], v[138:141], v[18:33]
	v_mfma_f32_32x32x16_bf16 v[18:33], v[14:17], v[142:145], v[18:33]
	v_mov_b32_e32 v53, v52
	s_nop 7
	s_nop 4
	v_pk_fma_f32 v[18:19], v[18:19], v[66:67], s[34:35] op_sel_hi:[1,0,1]
	v_pk_fma_f32 v[20:21], v[20:21], v[66:67], s[36:37] op_sel_hi:[1,0,1]
	v_pk_fma_f32 v[22:23], v[22:23], v[66:67], s[38:39] op_sel_hi:[1,0,1]
	v_pk_fma_f32 v[24:25], v[24:25], v[66:67], s[40:41] op_sel_hi:[1,0,1]
	v_pk_fma_f32 v[26:27], v[26:27], v[66:67], s[42:43] op_sel_hi:[1,0,1]
	v_pk_fma_f32 v[28:29], v[28:29], v[66:67], s[44:45] op_sel_hi:[1,0,1]
	v_pk_fma_f32 v[30:31], v[30:31], v[66:67], s[46:47] op_sel_hi:[1,0,1]
	v_pk_fma_f32 v[32:33], v[32:33], v[66:67], s[48:49] op_sel_hi:[1,0,1]
	v_cmp_le_i32_e64 s[16:17], 0, v54
	v_cmp_le_i32_e64 s[22:23], 1, v54
	v_cmp_le_i32_e64 s[24:25], 2, v54
	v_cmp_le_i32_e64 s[28:29], 3, v54
	v_cmp_le_i32_e32 vcc, 8, v54
	v_cndmask_b32_e64 v18, v67, v18, s[16:17]
	v_cndmask_b32_e64 v19, v67, v19, s[22:23]
	v_cndmask_b32_e64 v20, v67, v20, s[24:25]
	v_cndmask_b32_e64 v21, v67, v21, s[28:29]
	v_cndmask_b32_e64 v22, v67, v22, vcc
	v_cmp_le_i32_e64 s[16:17], 9, v54
	v_cmp_le_i32_e64 s[22:23], 10, v54
	v_cmp_le_i32_e64 s[24:25], 11, v54
	v_cmp_le_i32_e64 s[28:29], 16, v54
	v_cmp_le_i32_e32 vcc, 17, v54
	v_cndmask_b32_e64 v23, v67, v23, s[16:17]
	v_cndmask_b32_e64 v24, v67, v24, s[22:23]
	v_cndmask_b32_e64 v25, v67, v25, s[24:25]
	v_cndmask_b32_e64 v26, v67, v26, s[28:29]
	v_cndmask_b32_e64 v27, v67, v27, vcc
	v_cmp_le_i32_e64 s[16:17], 18, v54
	v_cmp_le_i32_e64 s[22:23], 19, v54
	v_cmp_le_i32_e64 s[24:25], 24, v54
	v_cmp_le_i32_e64 s[28:29], 25, v54
	v_cmp_le_i32_e32 vcc, 26, v54
	v_cndmask_b32_e64 v28, v67, v28, s[16:17]
	v_cndmask_b32_e64 v29, v67, v29, s[22:23]
	v_cndmask_b32_e64 v30, v67, v30, s[24:25]
	v_cndmask_b32_e64 v31, v67, v31, s[28:29]
	v_cndmask_b32_e64 v32, v67, v32, vcc
	v_cmp_le_i32_e64 s[16:17], 27, v54
	s_nop 1
	v_cndmask_b32_e64 v33, v67, v33, s[16:17]
	v_max3_f32 v183, v18, v19, v20
	v_max3_f32 v64, v21, v22, v23
	v_max3_f32 v60, v24, v25, v26
	v_max3_f32 v61, v27, v28, v29
	v_max3_f32 v68, v30, v31, v32
	v_max3_f32 v183, v183, v64, v60
	v_max3_f32 v61, v61, v68, v33
	v_max_f32_e32 v183, v183, v61
	v_add_f32_e32 v183, v183, v53
	v_mov_b32_e32 v64, v183
	s_nop 1
	v_permlane32_swap_b32_e32 v64, v183
	v_max_f32_e32 v183, v183, v64
	v_cmp_lt_f32_e32 vcc, v34, v183
	s_cbranch_vccz .Lband_keep4
	v_max_f32_e32 v64, v49, v183
	v_sub_f32_e32 v60, v49, v64
	v_exp_f32_e32 v60, v60
	v_mov_b32_e32 v49, v64
	v_add_f32_e32 v34, 0x41a00000, v64
	v_mul_f32_e32 v50, v50, v60
	v_pk_mul_f32 v[146:147], v[146:147], v[60:61] op_sel_hi:[1,0]
	v_pk_mul_f32 v[148:149], v[148:149], v[60:61] op_sel_hi:[1,0]
	v_pk_mul_f32 v[150:151], v[150:151], v[60:61] op_sel_hi:[1,0]
	v_pk_mul_f32 v[152:153], v[152:153], v[60:61] op_sel_hi:[1,0]
	v_pk_mul_f32 v[154:155], v[154:155], v[60:61] op_sel_hi:[1,0]
	v_pk_mul_f32 v[156:157], v[156:157], v[60:61] op_sel_hi:[1,0]
	v_pk_mul_f32 v[158:159], v[158:159], v[60:61] op_sel_hi:[1,0]
	v_pk_mul_f32 v[160:161], v[160:161], v[60:61] op_sel_hi:[1,0]
	v_pk_mul_f32 v[184:185], v[184:185], v[60:61] op_sel_hi:[1,0]
	v_pk_mul_f32 v[186:187], v[186:187], v[60:61] op_sel_hi:[1,0]
	v_pk_mul_f32 v[188:189], v[188:189], v[60:61] op_sel_hi:[1,0]
	v_pk_mul_f32 v[190:191], v[190:191], v[60:61] op_sel_hi:[1,0]
	v_pk_mul_f32 v[192:193], v[192:193], v[60:61] op_sel_hi:[1,0]
	v_pk_mul_f32 v[194:195], v[194:195], v[60:61] op_sel_hi:[1,0]
	v_pk_mul_f32 v[196:197], v[196:197], v[60:61] op_sel_hi:[1,0]
	v_pk_mul_f32 v[198:199], v[198:199], v[60:61] op_sel_hi:[1,0]
.Lband_keep4:
	v_sub_f32_e32 v68, v53, v49
	v_pk_add_f32 v[18:19], v[18:19], v[68:69] op_sel_hi:[1,0]
	v_exp_f32_e32 v18, v18
	v_exp_f32_e32 v19, v19
	v_pk_add_f32 v[20:21], v[20:21], v[68:69] op_sel_hi:[1,0]
	v_exp_f32_e32 v20, v20
	v_exp_f32_e32 v21, v21
	v_pk_add_f32 v[22:23], v[22:23], v[68:69] op_sel_hi:[1,0]
	v_exp_f32_e32 v22, v22
	v_exp_f32_e32 v23, v23
	v_pk_add_f32 v[24:25], v[24:25], v[68:69] op_sel_hi:[1,0]
	v_exp_f32_e32 v24, v24
	v_exp_f32_e32 v25, v25
	v_pk_add_f32 v[26:27], v[26:27], v[68:69] op_sel_hi:[1,0]
	v_exp_f32_e32 v26, v26
	v_exp_f32_e32 v27, v27
	v_pk_add_f32 v[28:29], v[28:29], v[68:69] op_sel_hi:[1,0]
	v_exp_f32_e32 v28, v28
	v_exp_f32_e32 v29, v29
	v_pk_add_f32 v[30:31], v[30:31], v[68:69] op_sel_hi:[1,0]
	v_exp_f32_e32 v30, v30
	v_exp_f32_e32 v31, v31
	v_pk_add_f32 v[32:33], v[32:33], v[68:69] op_sel_hi:[1,0]
	v_exp_f32_e32 v32, v32
	v_exp_f32_e32 v33, v33
	v_pk_add_f32 v[68:69], v[18:19], v[20:21]
	v_pk_add_f32 v[60:61], v[22:23], v[24:25]
	v_pk_add_f32 v[68:69], v[68:69], v[26:27]
	v_pk_add_f32 v[60:61], v[60:61], v[28:29]
	v_pk_add_f32 v[68:69], v[68:69], v[30:31]
	v_pk_add_f32 v[60:61], v[60:61], v[32:33]
	v_pk_add_f32 v[68:69], v[68:69], v[60:61]
	v_add_f32_e32 v183, v68, v69
	v_add_f32_e32 v50, v50, v183
	v_cvt_pk_bf16_f32 v18, v18, v19
	v_cvt_pk_bf16_f32 v19, v20, v21
	v_cvt_pk_bf16_f32 v20, v22, v23
	v_cvt_pk_bf16_f32 v21, v24, v25
	v_cvt_pk_bf16_f32 v22, v26, v27
	v_cvt_pk_bf16_f32 v23, v28, v29
	v_cvt_pk_bf16_f32 v24, v30, v31
	v_cvt_pk_bf16_f32 v25, v32, v33
	s_waitcnt vmcnt(0)
	s_nop 1
	v_mfma_f32_32x32x16_bf16 v[146:161], v[98:101], v[18:21], v[146:161]
	v_mfma_f32_32x32x16_bf16 v[184:199], v[106:109], v[18:21], v[184:199]
	v_mfma_f32_32x32x16_bf16 v[146:161], v[102:105], v[22:25], v[146:161]
	v_mfma_f32_32x32x16_bf16 v[184:199], v[110:113], v[22:25], v[184:199]
	s_nop 7
	s_nop 7
	v_mov_b32_e32 v64, v50
	s_nop 1
	v_permlane32_swap_b32_e32 v64, v50
	v_add_f32_e32 v50, v50, v64
	v_log_f32_e32 v183, v50
	v_rcp_f32_e32 v64, v50
	s_nop 0
	v_fma_f32 v60, -v50, v64, 1.0
	v_fma_f32 v64, v64, v60, v64
	v_add_f32_e32 v183, v49, v183
	v_mul_f32_e32 v183, 0x3f317218, v183
	s_cmp_eq_u32 s1, 0
	s_cbranch_scc1 .Lband_epi_swa
	v_mov_b32_e32 v60, v64
	v_cmp_eq_u32_e32 vcc, 0, v48
	s_and_saveexec_b64 s[16:17], vcc
	global_store_dword v63, v183, s[26:27]
	s_or_b64 exec, exec, s[16:17]
	s_branch .Lband_epi_scale
.Lband_epi_swa:
	s_waitcnt lgkmcnt(0)
	v_subrev_f32_e32 v183, s30, v183
	v_mul_f32_e32 v183, 0xbfb8aa3b, v183
	v_exp_f32_e32 v183, v183
	s_nop 0
	v_add_f32_e32 v183, 1.0, v183
	v_rcp_f32_e32 v60, v183
	s_nop 0
	v_fma_f32 v61, -v183, v60, 1.0
	v_fma_f32 v60, v60, v61, v60
	v_mul_f32_e32 v60, v60, v64
.Lband_epi_scale:
	v_pk_mul_f32 v[146:147], v[146:147], v[60:61] op_sel_hi:[1,0]
	v_pk_mul_f32 v[148:149], v[148:149], v[60:61] op_sel_hi:[1,0]
	v_pk_mul_f32 v[150:151], v[150:151], v[60:61] op_sel_hi:[1,0]
	v_pk_mul_f32 v[152:153], v[152:153], v[60:61] op_sel_hi:[1,0]
	v_pk_mul_f32 v[154:155], v[154:155], v[60:61] op_sel_hi:[1,0]
	v_pk_mul_f32 v[156:157], v[156:157], v[60:61] op_sel_hi:[1,0]
	v_pk_mul_f32 v[158:159], v[158:159], v[60:61] op_sel_hi:[1,0]
	v_pk_mul_f32 v[160:161], v[160:161], v[60:61] op_sel_hi:[1,0]
	v_pk_mul_f32 v[184:185], v[184:185], v[60:61] op_sel_hi:[1,0]
	v_pk_mul_f32 v[186:187], v[186:187], v[60:61] op_sel_hi:[1,0]
	v_pk_mul_f32 v[188:189], v[188:189], v[60:61] op_sel_hi:[1,0]
	v_pk_mul_f32 v[190:191], v[190:191], v[60:61] op_sel_hi:[1,0]
	v_pk_mul_f32 v[192:193], v[192:193], v[60:61] op_sel_hi:[1,0]
	v_pk_mul_f32 v[194:195], v[194:195], v[60:61] op_sel_hi:[1,0]
	v_pk_mul_f32 v[196:197], v[196:197], v[60:61] op_sel_hi:[1,0]
	v_pk_mul_f32 v[198:199], v[198:199], v[60:61] op_sel_hi:[1,0]
	v_cvt_pk_bf16_f32 v146, v146, v147
	v_cvt_pk_bf16_f32 v147, v148, v149
	global_store_dwordx2 v62, v[146:147], s[6:7]
	v_cvt_pk_bf16_f32 v150, v150, v151
	v_cvt_pk_bf16_f32 v151, v152, v153
	global_store_dwordx2 v62, v[150:151], s[6:7] offset:16
	v_cvt_pk_bf16_f32 v154, v154, v155
	v_cvt_pk_bf16_f32 v155, v156, v157
	global_store_dwordx2 v62, v[154:155], s[6:7] offset:32
	v_cvt_pk_bf16_f32 v158, v158, v159
	v_cvt_pk_bf16_f32 v159, v160, v161
	global_store_dwordx2 v62, v[158:159], s[6:7] offset:48
	v_cvt_pk_bf16_f32 v184, v184, v185
	v_cvt_pk_bf16_f32 v185, v186, v187
	global_store_dwordx2 v62, v[184:185], s[6:7] offset:64
	v_cvt_pk_bf16_f32 v188, v188, v189
	v_cvt_pk_bf16_f32 v189, v190, v191
	global_store_dwordx2 v62, v[188:189], s[6:7] offset:80
	v_cvt_pk_bf16_f32 v192, v192, v193
	v_cvt_pk_bf16_f32 v193, v194, v195
	global_store_dwordx2 v62, v[192:193], s[6:7] offset:96
	v_cvt_pk_bf16_f32 v196, v196, v197
	v_cvt_pk_bf16_f32 v197, v198, v199
	global_store_dwordx2 v62, v[196:197], s[6:7] offset:112
	s_add_i32 s0, s0, s68
	s_cmp_lt_u32 s0, 0x4000
	s_cbranch_scc1 .Lband_item
	v_lshlrev_b32_e32 v183, 2, v220
	v_add_u32_e32 v2, 0x10000, v183
	v_lshrrev_b32_e32 v183, 6, v220
	v_lshlrev_b32_e32 v183, 8, v183
	v_add_u32_e32 v183, 0x0, v183
	ds_read_b32 v2, v183 offset:0
	ds_read_b32 v3, v183 offset:4
	ds_read_b32 v4, v183 offset:8
	ds_read_b32 v5, v183 offset:12
	ds_read_b32 v6, v183 offset:16
	ds_read_b32 v7, v183 offset:20
	ds_read_b32 v8, v183 offset:24
	ds_read_b32 v9, v183 offset:28
	ds_read_b32 v10, v183 offset:32
	ds_read_b32 v11, v183 offset:36
	ds_read_b32 v12, v183 offset:40
	ds_read_b32 v13, v183 offset:44
	ds_read_b32 v14, v183 offset:48
	ds_read_b32 v15, v183 offset:52
	ds_read_b32 v16, v183 offset:56
	ds_read_b32 v17, v183 offset:60
	ds_read_b32 v18, v183 offset:64
	ds_read_b32 v19, v183 offset:68
	ds_read_b32 v20, v183 offset:72
	ds_read_b32 v21, v183 offset:76
	ds_read_b32 v22, v183 offset:80
	ds_read_b32 v23, v183 offset:84
	ds_read_b32 v24, v183 offset:88
	ds_read_b32 v25, v183 offset:92
	ds_read_b32 v26, v183 offset:96
	ds_read_b32 v27, v183 offset:100
	ds_read_b32 v28, v183 offset:104
	ds_read_b32 v29, v183 offset:108
	ds_read_b32 v30, v183 offset:112
	ds_read_b32 v31, v183 offset:116
	ds_read_b32 v32, v183 offset:120
	ds_read_b32 v33, v183 offset:124
	ds_read_b32 v34, v183 offset:128
	ds_read_b32 v35, v183 offset:132
	ds_read_b32 v36, v183 offset:136
	ds_read_b32 v37, v183 offset:140
	ds_read_b32 v38, v183 offset:144
	ds_read_b32 v39, v183 offset:148
	ds_read_b32 v40, v183 offset:152
	ds_read_b32 v41, v183 offset:156
	ds_read_b32 v42, v183 offset:160
	ds_read_b32 v43, v183 offset:164
	ds_read_b32 v44, v183 offset:168
	ds_read_b32 v45, v183 offset:172
	ds_read_b32 v46, v183 offset:176
	ds_read_b32 v47, v183 offset:180
	ds_read_b32 v48, v183 offset:184
	ds_read_b32 v49, v183 offset:188
	ds_read_b32 v50, v183 offset:192
	s_waitcnt lgkmcnt(0)
	v_readfirstlane_b32 s52, v50
	s_nop 3
	s_mov_b32 m0, s52
	v_readfirstlane_b32 s2, v2
	v_readfirstlane_b32 s3, v3
	v_readfirstlane_b32 s4, v4
	v_readfirstlane_b32 s5, v5
	v_readfirstlane_b32 s6, v6
	v_readfirstlane_b32 s7, v7
	v_readfirstlane_b32 s8, v8
	v_readfirstlane_b32 s9, v9
	v_readfirstlane_b32 s10, v10
	v_readfirstlane_b32 s11, v11
	v_readfirstlane_b32 s12, v12
	v_readfirstlane_b32 s13, v13
	v_readfirstlane_b32 s14, v14
	v_readfirstlane_b32 s15, v15
	v_readfirstlane_b32 s16, v16
	v_readfirstlane_b32 s17, v17
	v_readfirstlane_b32 s18, v18
	v_readfirstlane_b32 s19, v19
	v_readfirstlane_b32 s20, v20
	v_readfirstlane_b32 s21, v21
	v_readfirstlane_b32 s22, v22
	v_readfirstlane_b32 s23, v23
	v_readfirstlane_b32 s24, v24
	v_readfirstlane_b32 s25, v25
	v_readfirstlane_b32 s26, v26
	v_readfirstlane_b32 s27, v27
	v_readfirstlane_b32 s28, v28
	v_readfirstlane_b32 s29, v29
	v_readfirstlane_b32 s30, v30
	v_readfirstlane_b32 s34, v31
	v_readfirstlane_b32 s35, v32
	v_readfirstlane_b32 s36, v33
	v_readfirstlane_b32 s37, v34
	v_readfirstlane_b32 s38, v35
	v_readfirstlane_b32 s39, v36
	v_readfirstlane_b32 s40, v37
	v_readfirstlane_b32 s41, v38
	v_readfirstlane_b32 s42, v39
	v_readfirstlane_b32 s43, v40
	v_readfirstlane_b32 s44, v41
	v_readfirstlane_b32 s45, v42
	v_readfirstlane_b32 s46, v43
	v_readfirstlane_b32 s47, v44
	v_readfirstlane_b32 s48, v45
	v_readfirstlane_b32 s49, v46
	v_readfirstlane_b32 s50, v47
	v_readfirstlane_b32 s51, v48
	v_readfirstlane_b32 s52, v49
	s_waitcnt vmcnt(0)
	s_branch .Lband_exit
